# plain-GEMM job end: wait relaxed to vmcnt(16) so the 16 epilogue stores need not drain before the next job
# speedup vs baseline: 1.0033x; 1.0033x over previous
.LBB0_1144:
	s_waitcnt vmcnt(16)
	v_readlane_b32 s44, v253, 49
	v_readlane_b32 s46, v253, 47
	v_readlane_b32 s45, v253, 50
	v_readlane_b32 s80, v253, 53
	v_readlane_b32 s47, v253, 48
	v_readlane_b32 s81, v253, 54
	v_readlane_b32 s45, v253, 57
	s_movk_i32 s77, 0x100
	v_readlane_b32 s43, v249, 56
	s_mov_b32 s52, s57
	s_barrier
